# speedup vs baseline: 1.0054x; 1.0054x over previous
; DI int crow(int r, int hi) { return (r & 3) + 8 * (r >> 2) + 4 * hi; }
; DI float sigm(float x) { return __builtin_amdgcn_rcpf(1.f + __builtin_amdgcn_exp2f(-1.4426950408889634f * x)); }
; DI int tid_() { int t = threadIdx.x; asm volatile("" : "+v"(t)); return t; }
; #define HG_ISSUE(c) do { const int p_ = (c) * 32 + lt; const int tok_ = tokbase + (dir ? 511 - p_ : p_); const u16* rp_ = PROJ + (size_t)tok_ * INP + h * 128 + lc; \
;     rq = ld8(rp_ + C_HQ); rf = ld8(rp_ + fcol); rv = ld8(rp_ + C_HI); } while (0)
; #define HG_ISSUE(c) do { const int p_ = (c) * 64 + lt; const int tok_ = tokbase + (dir ? 511 - p_ : p_); const u16* rp_ = PROJ + (size_t)tok_ * INP + h * 128 + lc; \
;     if (MODE == 1) { rq0 = ld8(rp_ + C_HQ); rq1 = ld8(rp_ + C_HQ + 8); } rf0 = ld8(rp_ + fcol); rf1 = ld8(rp_ + fcol + 8); rv0 = ld8(rp_ + C_HI); rv1 = ld8(rp_ + C_HI + 8); } while (0)
; template <int MODE>
; DI void hgrn_item2(const u16* PROJ, int tokbase, int dir, int h, int layer, const float* hgrn_lb, float* Sg, float* Pg,
;                    u16* OH, const float* norm_g, char* lds) {
;   const int tid = tid_(), wid = tid >> 6, lane = tid & 63, r32 = lane & 31, hi = lane >> 5;
;   const int lt = tid >> 3, lc = (tid & 7) * 16;
;   const int bk = tid & 127, part = tid >> 7;
;   float lbv = 0.f;
;   if (layer > 0) { const int c = dir * 1024 + h * 128 + bk; lbv = sigm(hgrn_lb[2048 + c] - hgrn_lb[c]); }
;   const float oml = 1.f - lbv;
;   const int kb = wid >> 1, vbs = (wid & 1) * 2;
;   f32x16 S[2];
; #pragma unroll
;   for (int e = 0; e < 2; ++e) {
; #pragma unroll
;     for (int i = 0; i < 16; ++i) S[e][i] = (MODE == 1) ? Sg[(kb * 32 + crow(i, hi)) * 128 + (vbs + e) * 32 + r32] : 0.f; }
;   float logP = 0.f;
;   const int fcol = dir ? C_HFB : C_HFF;
;   bf16x8 rq0, rq1, rf0, rf1, rv0, rv1;
;     ...
;   HG_ISSUE(0);
.LBB0_65:
	s_lshl_b32 s6, s6, 3
	v_readlane_b32 s7, v255, 21
	s_add_i32 s6, s7, s6
	s_ashr_i32 s7, s6, 31
	v_readlane_b32 s12, v255, 36
	s_xor_b64 s[86:87], s[98:99], -1
	s_lshl_b64 s[6:7], s[6:7], s12
	v_ashrrev_i32_e32 v12, 6, v0
	s_add_u32 s6, s6, s89
	v_bfe_u32 v15, v0, 5, 1
	v_ashrrev_i32_e32 v74, 7, v0
	v_lshlrev_b32_e32 v2, 1, v12
	s_addc_u32 s7, s7, s2
	v_and_b32_e32 v14, 31, v0
	v_and_b32_e32 v75, 2, v2
	v_lshlrev_b32_e32 v119, 12, v74
	v_lshlrev_b32_e32 v2, 9, v15
	s_lshl_b64 s[6:7], s[6:7], 16
	v_readlane_b32 s12, v253, 18
	v_or3_b32 v16, v2, v119, v14
	v_lshlrev_b32_e32 v76, 5, v75
	s_add_u32 s6, s12, s6
	v_readlane_b32 s12, v253, 19
	v_or_b32_e32 v2, v16, v76
	s_addc_u32 s7, s12, s7
	v_ashrrev_i32_e32 v3, 31, v2
	v_lshl_add_u64 v[4:5], v[2:3], 2, s[6:7]
	s_movk_i32 s12, 0x1000
	v_add_co_u32_e32 v6, vcc, s12, v4
	s_movk_i32 s13, 0x2000
	s_nop 0
	v_addc_co_u32_e32 v7, vcc, 0, v5, vcc
	v_add_co_u32_e32 v8, vcc, s13, v4
	s_movk_i32 s36, 0x3000
	s_nop 0
	v_addc_co_u32_e32 v9, vcc, 0, v5, vcc
	v_add_co_u32_e32 v10, vcc, s36, v4
	v_ashrrev_i32_e32 v3, 31, v16
	s_nop 0
	v_addc_co_u32_e32 v11, vcc, 0, v5, vcc
	v_lshl_add_u64 v[2:3], v[2:3], 2, s[6:7]
	global_load_dword v36, v[8:9], off offset:1024
	global_load_dword v37, v[8:9], off offset:1536
	global_load_dword v44, v[4:5], off
	global_load_dword v45, v[4:5], off offset:512
	global_load_dword v42, v[4:5], off offset:1024
	global_load_dword v43, v[4:5], off offset:1536
	global_load_dword v41, v[6:7], off offset:512
	global_load_dword v38, v[6:7], off offset:1024
	global_load_dword v39, v[6:7], off offset:1536
	global_load_dword v34, v[10:11], off
	v_add_co_u32_e32 v4, vcc, s12, v2
	v_ashrrev_i32_e32 v72, 3, v0
	s_nop 0
	v_addc_co_u32_e32 v5, vcc, 0, v3, vcc
	v_add_co_u32_e32 v6, vcc, s13, v2
	global_load_dword v35, v[10:11], off offset:512
	global_load_dword v32, v[10:11], off offset:1024
	global_load_dword v33, v[10:11], off offset:1536
	global_load_dword v16, v[2:3], off offset:128
	global_load_dword v17, v[2:3], off offset:640
	global_load_dword v18, v[2:3], off offset:1152
	global_load_dword v19, v[2:3], off offset:1664
	global_load_dword v20, v[4:5], off offset:128
	v_addc_co_u32_e32 v7, vcc, 0, v3, vcc
	v_add_co_u32_e32 v2, vcc, s36, v2
	s_and_b64 s[6:7], s[98:99], exec
	s_nop 0
	v_addc_co_u32_e32 v3, vcc, 0, v3, vcc
	global_load_dword v21, v[4:5], off offset:640
	global_load_dword v22, v[4:5], off offset:1152
	global_load_dword v23, v[4:5], off offset:1664
	global_load_dword v24, v[6:7], off offset:128
	global_load_dword v25, v[6:7], off offset:640
	global_load_dword v26, v[6:7], off offset:1152
	global_load_dword v27, v[6:7], off offset:1664
	global_load_dword v28, v[2:3], off offset:128
	v_sub_u32_e32 v4, 0x1ff, v72
	v_cndmask_b32_e64 v4, v4, v72, s[98:99]
	v_and_b32_e32 v73, 7, v0
	s_movk_i32 s6, 0x400
	v_add_u32_e32 v6, s88, v4
	v_mov_b64_e32 v[4:5], s[94:95]
	s_cselect_b32 s6, s6, 0x800
	v_mad_i64_i32 v[4:5], s[36:37], v6, s33, v[4:5]
	v_lshlrev_b32_e32 v96, 5, v73
	v_lshl_add_u64 v[4:5], v[4:5], 0, v[96:97]
	s_lshl_b32 s84, s6, 1
	global_load_dword v29, v[2:3], off offset:640
	global_load_dword v30, v[2:3], off offset:1152
	global_load_dword v31, v[2:3], off offset:1664
	global_load_dwordx4 v[48:51], v[4:5], off
	v_lshl_add_u64 v[2:3], v[4:5], 0, s[84:85]
	global_load_dwordx4 v[52:55], v[4:5], off offset:16
	global_load_dwordx4 v[56:59], v[2:3], off
	v_add_co_u32_e32 v4, vcc, s12, v4
	v_readlane_b32 s48, v254, 31
	s_nop 0
	v_addc_co_u32_e32 v5, vcc, 0, v5, vcc
	global_load_dwordx4 v[60:63], v[2:3], off offset:16
	global_load_dwordx4 v[64:67], v[4:5], off offset:2048
	global_load_dword v40, v[8:9], off offset:-4096
	global_load_dword v46, v[8:9], off
	global_load_dword v47, v[8:9], off offset:512
	global_load_dwordx4 v[68:71], v[4:5], off offset:2064
	v_lshlrev_b32_e32 v3, 1, v72
	v_bitop3_b32 v2, v12, v0, 7 bitop3:0x78
	v_and_b32_e32 v3, 14, v3
	v_lshl_or_b32 v5, v2, 4, v3
	v_lshlrev_b32_e32 v2, 1, v1
	v_readlane_b32 s49, v254, 32
	v_add_u32_e32 v121, 16, v2
	v_add_u32_e32 v6, s48, v2
	v_mov_b32_e32 v2, s49
	s_movk_i32 s74, 0x90
	v_lshlrev_b32_e32 v3, 2, v1
	v_mad_u32_u24 v7, v1, s74, v2
	v_lshlrev_b32_e32 v1, 5, v12
	v_readlane_b32 s7, v254, 30
	s_movk_i32 s12, 0xffe0
	v_and_b32_e32 v1, 0x60, v1
	v_lshlrev_b32_e32 v10, 2, v15
	v_lshl_add_u32 v122, v0, 2, s7
	v_add_u32_e32 v123, s7, v3
	s_movk_i32 s7, 0x80
	v_bfi_b32 v126, s12, v72, v0
	v_or3_b32 v90, s92, v1, v10
	v_readlane_b32 s12, v253, 20
	v_cmp_eq_u32_e32 vcc, 2, v12
	v_cmp_gt_u32_e64 s[42:43], s7, v0
	v_readlane_b32 s7, v254, 33
	v_readlane_b32 s75, v254, 34
	v_ashrrev_i32_e32 v91, 31, v90
	v_readlane_b32 s13, v253, 21
	v_cndmask_b32_e64 v1, 0, 32, vcc
	v_add_u32_e32 v124, s7, v3
	v_add_u32_e32 v125, s75, v3
	v_lshl_add_u64 v[92:93], v[90:91], 1, s[12:13]
	v_or_b32_e32 v3, v1, v14
	v_mov_b32_e32 v77, s48
	s_movk_i32 s12, 0x110
	v_cmp_lt_i32_e32 vcc, 0, v12
	v_mad_u32_u24 v77, v3, s12, v77
	v_cmp_lt_i32_e64 s[44:45], 2, v12
	v_cndmask_b32_e64 v3, 0, 32, vcc
	v_cmp_eq_u32_e64 s[46:47], 3, v12
	v_or_b32_e32 v78, v3, v14
	v_and_b32_e32 v12, 3, v12
	v_mad_u32_u24 v128, v78, s12, 16
	v_or_b32_e32 v79, v1, v10
	v_lshlrev_b32_e32 v1, 7, v78
	v_lshlrev_b32_e32 v82, 5, v12
	v_readlane_b32 s13, v254, 35
	v_sub_u32_e32 v80, v128, v1
	v_or_b32_e32 v1, v82, v14
	v_mov_b32_e32 v83, s13
	v_mul_lo_u32 v3, v126, s12
	v_lshlrev_b32_e32 v8, 5, v74
	v_mad_u32_u24 v84, v1, s12, v83
	v_add_u32_e32 v129, 16, v3
	v_mad_u32_u24 v85, v1, s74, 16
	v_lshlrev_b32_e32 v1, 7, v126
	s_waitcnt vmcnt(45)
; template <int MODE>
; DI void hgrn_item2(const u16* PROJ, int tokbase, int dir, int h, int layer, const float* hgrn_lb, float* Sg, float* Pg,
;                    u16* OH, const float* norm_g, char* lds) {
;     ...
;         for (int d0 = 0; d0 < 8; ++d0) {
;           const bf16x8 a = *reinterpret_cast<const bf16x8*>(lds + HL_KSK + (sb * 32 + r32) * 272 + d0 * 32 + hi * 16);
;           const bf16x8 b = *reinterpret_cast<const bf16x8*>(lds + HL_QT + (tb * 32 + r32) * 272 + d0 * 32 + hi * 16);
;           pa = __builtin_amdgcn_mfma_f32_32x32x16_bf16(a, b, pa, 0, 0, 0); }
;         const int t = tb * 32 + r32;
; #pragma unroll
;         for (int q4 = 0; q4 < 4; ++q4) { const int s0 = sb * 32 + 8 * q4 + 4 * hi;
;           *reinterpret_cast<uint2*>(lds + HL_RAWQ + t * 144 + s0 * 2) =
;             pack4(s0 <= t ? pa[4 * q4] : 0.f, s0 + 1 <= t ? pa[4 * q4 + 1] : 0.f, s0 + 2 <= t ? pa[4 * q4 + 2] : 0.f, s0 + 3 <= t ? pa[4 * q4 + 3] : 0.f); }
;       } else if (wid == 3) {
; #pragma unroll
;         for (int q4 = 0; q4 < 4; ++q4) *reinterpret_cast<uint2*>(lds + HL_RAWQ + r32 * 144 + (32 + 8 * q4 + 4 * hi) * 2) = make_uint2(0u, 0u);
;       }
;     }
; #pragma unroll
;     for (int e = 0; e < 2; ++e) {
; #pragma unroll
;       for (int q4 = 0; q4 < 4; ++q4) { const int k0 = kb * 32 + 8 * q4 + 4 * hi;
;         const float4 er = *reinterpret_cast<const float4*>(lds + HL_ER + k0 * 4);
;         S[e][4 * q4] *= er.x; S[e][4 * q4 + 1] *= er.y; S[e][4 * q4 + 2] *= er.z; S[e][4 * q4 + 3] *= er.w;
;         if (MODE == 1) *reinterpret_cast<uint2*>(lds + HL_ST + ((vbs + e) * 32 + r32) * 272 + k0 * 2) = pack4(S[e][4 * q4], S[e][4 * q4 + 1], S[e][4 * q4 + 2], S[e][4 * q4 + 3]); } }
;     f32x16 oa = {0.f, 0.f, 0.f, 0.f, 0.f, 0.f, 0.f, 0.f, 0.f, 0.f, 0.f, 0.f, 0.f, 0.f, 0.f, 0.f};
;     const int vb = wid & 3, tb2 = wid >> 2;
;     if (MODE == 1) {
;       __syncthreads();
; #pragma unroll
;       for (int d0 = 0; d0 < 8; ++d0) {
;         const bf16x8 a = *reinterpret_cast<const bf16x8*>(lds + HL_ST + (vb * 32 + r32) * 272 + d0 * 32 + hi * 16);
;         const bf16x8 b = *reinterpret_cast<const bf16x8*>(lds + HL_QT + (tb2 * 32 + r32) * 272 + d0 * 32 + hi * 16);
;         oa = __builtin_amdgcn_mfma_f32_32x32x16_bf16(a, b, oa, 0, 0, 0); }
; #pragma unroll
;       for (int s0 = 0; s0 < 4; ++s0) {
	v_sub_u32_e32 v100, v129, v1
	v_or_b32_e32 v1, v8, v14
	v_and_b32_e32 v13, 63, v0
	v_bfe_u32 v87, v0, 4, 1
	v_mul_lo_u32 v1, v1, s74
	v_and_b32_e32 v0, 0xffffff80, v0
	v_add_u32_e32 v101, s49, v1
	s_waitcnt vmcnt(44)
	v_add_u32_e32 v102, s7, v0
	v_lshlrev_b32_e32 v0, 6, v12
	v_mov_b32_e32 v1, v97
	v_lshlrev_b32_e32 v2, 3, v15
	v_lshl_add_u64 v[0:1], s[96:97], 0, v[0:1]
	v_mov_b32_e32 v3, v97
	v_readlane_b32 s7, v254, 36
	v_lshl_add_u64 v[94:95], v[0:1], 0, v[2:3]
	v_or_b32_e32 v1, 2, v79
	v_lshl_add_u32 v131, v126, 2, s7
	v_lshlrev_b32_e32 v86, 1, v12
	v_lshl_add_u32 v132, v12, 8, v131
	v_cmp_gt_u32_e64 s[54:55], v1, v78
	v_or_b32_e32 v1, 3, v79
	v_or_b32_e32 v12, 10, v79
	v_lshlrev_b32_e32 v0, 2, v13
	v_cmp_gt_u32_e64 s[48:49], 32, v13
	v_cmp_gt_u32_e64 s[56:57], v1, v78
	v_or_b32_e32 v1, 8, v79
	v_cmp_gt_u32_e64 s[62:63], v12, v78
	v_or_b32_e32 v12, 11, v79
	v_or_b32_e32 v13, 18, v79
	v_or_b32_e32 v81, v10, v8
	v_cmp_gt_u32_e64 s[58:59], v1, v78
	v_cmp_lt_u32_e64 s[60:61], v1, v78
	v_cmp_gt_u32_e64 s[64:65], v12, v78
	v_lshlrev_b32_e32 v12, 1, v1
	v_or_b32_e32 v1, 16, v79
	v_cmp_gt_u32_e64 s[70:71], v13, v78
	v_or_b32_e32 v13, 19, v79
	v_cmp_gt_u32_e64 s[66:67], v1, v78
	v_cmp_lt_u32_e64 s[68:69], v1, v78
	v_cmp_gt_u32_e64 s[72:73], v13, v78
	v_lshlrev_b32_e32 v13, 1, v1
	v_or_b32_e32 v1, v76, v14
	v_or_b32_e32 v76, 8, v81
	s_waitcnt vmcnt(43)
	v_lshlrev_b32_e32 v104, 2, v76
	v_lshlrev_b32_e32 v136, 1, v76
	v_or_b32_e32 v76, 16, v81
	v_lshlrev_b32_e32 v105, 2, v76
	v_lshlrev_b32_e32 v137, 1, v76
	v_or_b32_e32 v76, 24, v81
	v_lshlrev_b32_e32 v103, 2, v81
	v_lshlrev_b32_e32 v135, 1, v81
	v_lshlrev_b32_e32 v81, 2, v76
	v_lshlrev_b32_e32 v138, 1, v76
	v_or_b32_e32 v76, 32, v1
	v_mad_u32_u24 v134, v1, s12, v83
	v_mad_u32_u24 v139, v76, s12, v83
	v_or_b32_e32 v83, 2, v15
	v_bitop3_b32 v98, v86, v83, v87 bitop3:0x36
	s_waitcnt vmcnt(42)
	v_lshlrev_b32_e32 v106, 4, v98
	v_or_b32_e32 v98, 4, v15
	v_bitop3_b32 v99, v86, v98, v87 bitop3:0x36
	v_lshlrev_b32_e32 v107, 4, v99
	v_or_b32_e32 v99, 6, v15
	s_waitcnt vmcnt(38)
	v_mad_u32_u24 v108, v1, s74, 16
	v_lshlrev_b32_e32 v1, 1, v75
	v_bitop3_b32 v109, v1, v15, v87 bitop3:0x36
	v_bitop3_b32 v110, v1, v83, v87 bitop3:0x36
	v_bitop3_b32 v111, v1, v98, v87 bitop3:0x36
	v_bitop3_b32 v1, v1, v99, v87 bitop3:0x36
	s_movk_i32 s7, 0x900
	v_lshlrev_b32_e32 v112, 4, v1
	v_or_b32_e32 v1, 1, v75
	v_mad_u32_u24 v3, v73, s7, 16
	s_movk_i32 s7, 0x1100
	v_lshl_or_b32 v75, v1, 5, v14
	v_lshlrev_b32_e32 v1, 1, v1
	v_lshlrev_b32_e32 v127, 4, v15
	v_xor_b32_e32 v130, 0x80, v0
	v_or3_b32 v0, v10, s92, v82
	v_mul_lo_u32 v133, v74, s7
	s_lshl_b32 s84, s6, 1
	v_bitop3_b32 v76, v86, v15, v87 bitop3:0x36
	v_bitop3_b32 v15, v1, v15, v87 bitop3:0x36
	v_bitop3_b32 v83, v1, v83, v87 bitop3:0x36
	v_bitop3_b32 v98, v1, v98, v87 bitop3:0x36
	v_bitop3_b32 v1, v1, v99, v87 bitop3:0x36
	v_readlane_b32 s6, v255, 37
	v_or_b32_e32 v73, 24, v79
	v_bitop3_b32 v86, v86, v99, v87 bitop3:0x36
	v_lshlrev_b32_e32 v87, 4, v1
	v_ashrrev_i32_e32 v1, 31, v0
	v_readlane_b32 s7, v255, 38
	v_lshl_add_u32 v4, v72, 8, 16
	v_cmp_lt_i32_e64 s[36:37], 0, v74
	v_cmp_lt_i32_e64 s[38:39], 1, v74
	v_cmp_lt_i32_e64 s[40:41], 2, v74
	v_and_b32_e32 v9, 0xffffffe0, v72
	v_mad_u32_u24 v11, v14, s74, 16
	v_cmp_gt_u32_e64 s[50:51], v79, v78
	v_cmp_lt_u32_e64 s[52:53], v79, v78
	v_lshlrev_b32_e32 v10, 1, v79
	v_or_b32_e32 v74, 26, v79
	v_or_b32_e32 v79, 27, v79
	v_lshlrev_b32_e32 v82, 1, v73
	v_lshlrev_b32_e32 v76, 4, v76
	v_lshlrev_b32_e32 v86, 4, v86
	v_lshlrev_b32_e32 v109, 4, v109
	v_lshlrev_b32_e32 v110, 4, v110
	v_lshlrev_b32_e32 v111, 4, v111
	v_mad_u32_u24 v75, v75, s74, 16
	v_lshlrev_b32_e32 v15, 4, v15
	v_lshlrev_b32_e32 v83, 4, v83
	v_lshlrev_b32_e32 v113, 4, v98
	v_lshl_add_u64 v[98:99], v[0:1], 2, s[6:7]
	global_load_dwordx4 v[198:201], v[98:99], off
	global_load_dwordx4 v[202:205], v[98:99], off offset:32
	global_load_dwordx4 v[206:209], v[98:99], off offset:64
	global_load_dwordx4 v[210:213], v[98:99], off offset:96
	v_sub_u32_e32 v0, s93, v14
	s_mov_b32 s90, 0
	v_sub_f32_e32 v120, 1.0, v118
	v_lshl_add_u64 v[88:89], s[94:95], 0, v[96:97]
	v_sub_u32_e32 v140, v0, v9
	v_sub_u32_e32 v141, 0x1ff, v126
	v_add_u32_e32 v142, 64, v72
	v_sub_u32_e32 v143, 0x1bf, v72
	v_add_u32_e32 v96, v4, v96
	v_add_u32_e32 v144, v3, v5
	v_add_u32_e32 v145, v6, v133
	v_add_u32_e32 v146, v7, v8
	v_add_u32_e32 v147, v11, v2
	v_add_u32_e32 v148, v77, v127
	v_add_u32_e32 v149, v80, v10
	v_add_u32_e32 v150, v80, v12
	v_add_u32_e32 v151, v80, v13
	v_add_u32_e32 v152, v80, v82
	v_add_u32_e32 v153, v84, v127
	v_add_u32_e32 v154, v85, v76
	v_add_u32_e32 v155, v100, v127
	v_add_u32_e32 v156, v85, v106
	v_add_u32_e32 v157, v85, v107
	v_add_u32_e32 v158, v85, v86
	v_add_u32_e32 v159, v101, v127
	v_add_u32_e32 v160, v108, v109
	v_add_u32_e32 v161, v108, v110
	v_add_u32_e32 v162, v108, v111
	v_add_u32_e32 v163, v108, v112
	v_add_u32_e32 v164, v75, v15
	v_add_u32_e32 v165, v75, v83
	v_add_u32_e32 v166, v75, v113
	v_add_u32_e32 v167, v75, v87
	v_add_u32_e32 v168, v102, v127
	v_add_u32_e32 v169, s75, v103
	v_add_u32_e32 v170, s75, v104
	v_add_u32_e32 v171, s75, v105
	v_add_u32_e32 v172, s75, v81
	v_cmp_gt_u32_e64 s[74:75], v73, v78
	v_cmp_lt_u32_e64 s[76:77], v73, v78
	v_cmp_gt_u32_e64 s[78:79], v74, v78
	v_cmp_gt_u32_e64 s[80:81], v79, v78
	s_branch .LBB0_67

; DI uint2 pack4(float a, float b, float c, float d) { return make_uint2(cvtpk(a, b), cvtpk(c, d)); }
; DI float sigm(float x) { return __builtin_amdgcn_rcpf(1.f + __builtin_amdgcn_exp2f(-1.4426950408889634f * x)); }
; template <int MODE>
; DI void hgrn_item2(const u16* PROJ, int tokbase, int dir, int h, int layer, const float* hgrn_lb, float* Sg, float* Pg,
;                    u16* OH, const float* norm_g, char* lds) {
;     ...
;         float ss = 0.f;
; #pragma unroll
;         for (int q4 = 0; q4 < 4; ++q4) { const uint2 t8 = pf_t[q4];
;           oa[4 * q4] += __uint_as_float(t8.x << 16); oa[4 * q4 + 1] += __uint_as_float(t8.x & 0xffff0000u);
;           oa[4 * q4 + 2] += __uint_as_float(t8.y << 16); oa[4 * q4 + 3] += __uint_as_float(t8.y & 0xffff0000u);
;           ss += oa[4 * q4] * oa[4 * q4] + oa[4 * q4 + 1] * oa[4 * q4 + 1] + oa[4 * q4 + 2] * oa[4 * q4 + 2] + oa[4 * q4 + 3] * oa[4 * q4 + 3]; }
;         ss += __int_as_float(__builtin_amdgcn_ds_bpermute((lane ^ 32) << 2, __float_as_int(ss)));
;         if (hi == 0) reinterpret_cast<float*>(lds + HL_SS)[vb * 64 + t] = ss;
;         __syncthreads();
;         const float* ssp = reinterpret_cast<const float*>(lds + HL_SS) + t;
;         const float rn = rsqrtf((ssp[0] + ssp[64] + ssp[128] + ssp[192]) * (1.f / 128.f) + EPS);
; #pragma unroll
;         for (int q4 = 0; q4 < 4; ++q4) { const int cv = h * 128 + vb * 32 + 4 * hi + 8 * q4;
;           const uint2 hg = pf_g[q4]; const float4 ng = *reinterpret_cast<const float4*>(norm_g + cv);
;           const float h0 = __uint_as_float(hg.x << 16), h1 = __uint_as_float(hg.x & 0xffff0000u), h2 = __uint_as_float(hg.y << 16), h3 = __uint_as_float(hg.y & 0xffff0000u);
;           *reinterpret_cast<uint2*>(op + 8 * q4) = pack4(oa[4 * q4] * rn * ng.x * (h0 * sigm(h0)), oa[4 * q4 + 1] * rn * ng.y * (h1 * sigm(h1)),
;                                                          oa[4 * q4 + 2] * rn * ng.z * (h2 * sigm(h2)), oa[4 * q4 + 3] * rn * ng.w * (h3 * sigm(h3))); }
.LBB0_78:
	s_or_b64 exec, exec, s[6:7]
	s_waitcnt lgkmcnt(0)
	s_barrier
	ds_read2st64_b32 v[190:191], v131 offset1:1
	s_waitcnt vmcnt(3)
	v_lshlrev_b32_e32 v194, 16, v114
	v_and_b32_e32 v195, 0xffff0000, v114
	v_lshlrev_b32_e32 v196, 16, v115
	v_and_b32_e32 v197, 0xffff0000, v115
	s_waitcnt lgkmcnt(0)
	v_add_f32_e32 v175, v190, v191
	ds_read2st64_b32 v[190:191], v131 offset0:2 offset1:3
	s_mov_b64 s[6:7], 0
	s_waitcnt lgkmcnt(0)
	v_add_f32_e32 v175, v175, v190
	v_add_f32_e32 v175, v175, v191
	v_fmamk_f32 v175, v175, 0x3c000000, v233
	v_cmp_gt_f32_e32 vcc, s91, v175
	v_mul_f32_e32 v190, 0x4b800000, v175
	s_nop 0
	v_cndmask_b32_e32 v175, v175, v190, vcc
	v_rsq_f32_e32 v175, v175
	s_nop 0
	v_mul_f32_e32 v190, 0x45800000, v175
	v_cndmask_b32_e32 v175, v175, v190, vcc
	v_mul_f32_e32 v189, v189, v175
	v_mul_f32_e32 v188, v188, v175
	v_mul_f32_e32 v187, v187, v175
	v_mul_f32_e32 v186, v186, v175
	v_mul_f32_e32 v185, v185, v175
	v_mul_f32_e32 v184, v184, v175
	v_mul_f32_e32 v183, v183, v175
	v_mul_f32_e32 v182, v182, v175
	v_mul_f32_e32 v181, v181, v175
	v_mul_f32_e32 v180, v180, v175
	v_mul_f32_e32 v179, v179, v175
	v_mul_f32_e32 v178, v178, v175
	v_mul_f32_e32 v177, v177, v175
	v_mul_f32_e32 v176, v176, v175
	v_mul_f32_e32 v174, v174, v175
	v_mul_f32_e32 v173, v173, v175
	s_waitcnt vmcnt(0)
	v_mul_f32_e32 v189, v198, v189
	v_mul_f32_e32 v190, 0xbfb8aa3b, v194
	v_exp_f32_e32 v190, v190
	v_mul_f32_e32 v188, v199, v188
	v_mul_f32_e32 v187, v200, v187
	v_mul_f32_e32 v186, v201, v186
	v_add_f32_e32 v190, 1.0, v190
	v_rcp_f32_e32 v190, v190
	v_and_b32_e32 v191, 0xffff0000, v112
	v_lshlrev_b32_e32 v192, 16, v113
	v_and_b32_e32 v193, 0xffff0000, v113
	v_mul_f32_e32 v190, v190, v194
	v_mul_f32_e32 v189, v190, v189
	v_mul_f32_e32 v190, 0xbfb8aa3b, v195
	v_exp_f32_e32 v190, v190
	s_nop 0
	v_add_f32_e32 v190, 1.0, v190
	v_rcp_f32_e32 v190, v190
	s_nop 0
	v_mul_f32_e32 v190, v190, v195
	v_mul_f32_e32 v188, v190, v188
	v_mul_f32_e32 v190, 0xbfb8aa3b, v196
	v_exp_f32_e32 v190, v190
	s_nop 0
	v_add_f32_e32 v190, 1.0, v190
	v_rcp_f32_e32 v190, v190
	s_nop 0
	v_mul_f32_e32 v190, v190, v196
	v_mul_f32_e32 v187, v190, v187
	v_mul_f32_e32 v190, 0xbfb8aa3b, v197
	v_exp_f32_e32 v190, v190
	s_nop 0
	v_add_f32_e32 v190, 1.0, v190
	v_rcp_f32_e32 v190, v190
	s_nop 0
	v_mul_f32_e32 v190, v190, v197
	v_mul_f32_e32 v190, v190, v186
	v_cvt_pk_bf16_f32 v186, v189, v188
	v_cvt_pk_bf16_f32 v187, v187, v190
	global_store_dwordx2 v[116:117], v[186:187], off
	v_lshlrev_b32_e32 v190, 16, v112
	v_mul_f32_e32 v185, v185, v202
	v_mul_f32_e32 v186, 0xbfb8aa3b, v190
	v_exp_f32_e32 v186, v186
	v_mul_f32_e32 v184, v184, v203
	v_mul_f32_e32 v183, v183, v204
	v_mul_f32_e32 v182, v182, v205
	v_add_f32_e32 v186, 1.0, v186
	v_rcp_f32_e32 v186, v186
	v_and_b32_e32 v187, 0xffff0000, v110
	v_lshlrev_b32_e32 v188, 16, v111
	v_and_b32_e32 v189, 0xffff0000, v111
	v_mul_f32_e32 v186, v186, v190
	v_mul_f32_e32 v185, v186, v185
	v_mul_f32_e32 v186, 0xbfb8aa3b, v191
	v_exp_f32_e32 v186, v186
	s_nop 0
	v_add_f32_e32 v186, 1.0, v186
	v_rcp_f32_e32 v186, v186
	s_nop 0
	v_mul_f32_e32 v186, v186, v191
	v_mul_f32_e32 v184, v186, v184
	v_mul_f32_e32 v186, 0xbfb8aa3b, v192
	v_exp_f32_e32 v186, v186
	s_nop 0
	v_add_f32_e32 v186, 1.0, v186
	v_rcp_f32_e32 v186, v186
	s_nop 0
	v_mul_f32_e32 v186, v186, v192
	v_mul_f32_e32 v183, v186, v183
	v_mul_f32_e32 v186, 0xbfb8aa3b, v193
	v_exp_f32_e32 v186, v186
	s_nop 0
	v_add_f32_e32 v186, 1.0, v186
	v_rcp_f32_e32 v186, v186
	s_nop 0
	v_mul_f32_e32 v186, v186, v193
	v_mul_f32_e32 v186, v186, v182
	v_cvt_pk_bf16_f32 v182, v185, v184
	v_cvt_pk_bf16_f32 v183, v183, v186
	global_store_dwordx2 v[116:117], v[182:183], off offset:16
	v_lshlrev_b32_e32 v186, 16, v110
	v_mul_f32_e32 v181, v181, v206
	v_mul_f32_e32 v182, 0xbfb8aa3b, v186
	v_exp_f32_e32 v182, v182
	v_mul_f32_e32 v180, v180, v207
	v_mul_f32_e32 v179, v179, v208
	v_mul_f32_e32 v178, v178, v209
	v_add_f32_e32 v182, 1.0, v182
	v_rcp_f32_e32 v182, v182
	v_and_b32_e32 v183, 0xffff0000, v108
	v_lshlrev_b32_e32 v184, 16, v109
	v_and_b32_e32 v185, 0xffff0000, v109
	v_mul_f32_e32 v182, v182, v186
	v_mul_f32_e32 v181, v182, v181
	v_mul_f32_e32 v182, 0xbfb8aa3b, v187
	v_exp_f32_e32 v182, v182
	s_nop 0
	v_add_f32_e32 v182, 1.0, v182
	v_rcp_f32_e32 v182, v182
	s_nop 0
	v_mul_f32_e32 v182, v182, v187
	v_mul_f32_e32 v180, v182, v180
	v_mul_f32_e32 v182, 0xbfb8aa3b, v188
	v_exp_f32_e32 v182, v182
	s_nop 0
	v_add_f32_e32 v182, 1.0, v182
	v_rcp_f32_e32 v182, v182
	s_nop 0
	v_mul_f32_e32 v182, v182, v188
	v_mul_f32_e32 v179, v182, v179
	v_mul_f32_e32 v182, 0xbfb8aa3b, v189
	v_exp_f32_e32 v182, v182
	s_nop 0
	v_add_f32_e32 v182, 1.0, v182
	v_rcp_f32_e32 v182, v182
	s_nop 0
	v_mul_f32_e32 v182, v182, v189
	v_mul_f32_e32 v182, v182, v178
	v_cvt_pk_bf16_f32 v178, v181, v180
	v_cvt_pk_bf16_f32 v179, v179, v182
	global_store_dwordx2 v[116:117], v[178:179], off offset:32
	v_lshlrev_b32_e32 v182, 16, v108
	v_mul_f32_e32 v177, v177, v210
	v_mul_f32_e32 v178, 0xbfb8aa3b, v182
	v_exp_f32_e32 v178, v178
	v_mul_f32_e32 v176, v176, v211
	v_mul_f32_e32 v174, v174, v212
	v_mul_f32_e32 v173, v173, v213
	v_add_f32_e32 v178, 1.0, v178
	v_rcp_f32_e32 v178, v178
	s_nop 0
	v_mul_f32_e32 v178, v178, v182
	v_mul_f32_e32 v177, v178, v177
	v_mul_f32_e32 v178, 0xbfb8aa3b, v183
	v_exp_f32_e32 v178, v178
	s_nop 0
	v_add_f32_e32 v178, 1.0, v178
	v_rcp_f32_e32 v178, v178
	s_nop 0
	v_mul_f32_e32 v178, v178, v183
	v_mul_f32_e32 v176, v178, v176
	v_mul_f32_e32 v178, 0xbfb8aa3b, v184
	v_exp_f32_e32 v178, v178
	s_nop 0
	v_add_f32_e32 v178, 1.0, v178
	v_rcp_f32_e32 v178, v178
	s_nop 0
	v_mul_f32_e32 v178, v178, v184
	v_mul_f32_e32 v178, v178, v174
	v_mul_f32_e32 v174, 0xbfb8aa3b, v185
	v_exp_f32_e32 v174, v174
	s_nop 0
	v_add_f32_e32 v174, 1.0, v174
	v_rcp_f32_e32 v174, v174
	s_nop 0
	v_mul_f32_e32 v174, v174, v185
	v_mul_f32_e32 v173, v174, v173
	v_cvt_pk_bf16_f32 v174, v177, v176
	v_cvt_pk_bf16_f32 v175, v178, v173
	global_store_dwordx2 v[116:117], v[174:175], off offset:48

; #define QK_FENCE() __builtin_amdgcn_sched_barrier(0x406)
; DI void finishSM(f32x16& p0, f32x16& p1, float alpha, float& l_reg, bf16x8& pa0, bf16x8& pa1, bf16x8& pa2, bf16x8& pa3) {
; #pragma unroll
;   for (int r = 0; r < 16; ++r) p1[r] = __builtin_amdgcn_exp2f(p1[r]);
;   float ps = 0;
; #pragma unroll
;   for (int r = 0; r < 16; ++r) ps += p0[r];
; #pragma unroll
;   for (int r = 0; r < 16; ++r) ps += p1[r];
;   { auto rr = __builtin_amdgcn_permlane32_swap(__float_as_uint(ps), __float_as_uint(ps), false, false);
;     ps = __uint_as_float(rr[0]) + __uint_as_float(rr[1]); }
;   l_reg = l_reg * alpha + ps;
;     ...
;   PK4(p0, 0, pa0); PK4(p0, 8, pa1); PK4(p1, 0, pa2); PK4(p1, 8, pa3);
; DI void qkt12(f32x16& p0, f32x16& p1, const char* Kt, const char* Rt, const int* ko, const int* ro, const bf16x8* qr) {
;   { const f32x16 z = {0.f, 0.f, 0.f, 0.f, 0.f, 0.f, 0.f, 0.f, 0.f, 0.f, 0.f, 0.f, 0.f, 0.f, 0.f, 0.f}; p0 = z; p1 = z; }
;   const char* kp[4] = {Kt + ko[0], Kt + ko[1], Kt + ko[2], Kt + ko[3]};
;   const char* rp[4] = {Rt + ro[0], Rt + ro[1], Rt + ro[2], Rt + ro[3]};
;   bf16x8 ka[2], kb[2];
;   ka[0] = *reinterpret_cast<const bf16x8*>(kp[0]); kb[0] = *reinterpret_cast<const bf16x8*>(kp[0] + 8192);
; #pragma unroll
;   for (int d0 = 0; d0 < 12; ++d0) {
;     if (d0 + 1 < 12) { const int d1 = d0 + 1;
;       if (d1 < 8) { ka[d1 & 1] = *reinterpret_cast<const bf16x8*>(kp[d1 & 3] + (d1 >> 2) * 128); kb[d1 & 1] = *reinterpret_cast<const bf16x8*>(kp[d1 & 3] + (d1 >> 2) * 128 + 8192); }
;       else { ka[d1 & 1] = *reinterpret_cast<const bf16x8*>(rp[d1 - 8]); kb[d1 & 1] = *reinterpret_cast<const bf16x8*>(rp[d1 - 8] + 4096); } }
;     QK_FENCE();
;     p0 = __builtin_amdgcn_mfma_f32_32x32x16_bf16(ka[d0 & 1], qr[d0], p0, 0, 0, 0);
;     p1 = __builtin_amdgcn_mfma_f32_32x32x16_bf16(kb[d0 & 1], qr[d0], p1, 0, 0, 0);
;     QK_FENCE();
;   }
.LBB0_122:
	v_sub_co_u32_e64 v64, s[6:7], s61, 1
	s_and_b64 s[6:7], s[6:7], exec
	v_readfirstlane_b32 s2, v64
	s_cselect_b32 s13, 2, s2
	s_mul_i32 s42, s61, 0xa000
	s_add_i32 s45, s42, 16
	v_add_u32_e32 v177, s45, v176
	ds_read_b128 v[64:67], v177 offset:16384
	v_add_u32_e32 v220, s45, v179
	ds_read_b128 v[68:71], v177 offset:24576
	ds_read_b128 v[188:191], v220 offset:16384
	ds_read_b128 v[208:211], v220 offset:24576
	v_add_u32_e32 v221, s45, v180
	v_add_u32_e32 v222, s45, v181
	v_exp_f32_e32 v200, v200
	v_exp_f32_e32 v202, v202
	v_exp_f32_e32 v201, v201
	v_exp_f32_e32 v204, v204
	v_exp_f32_e32 v203, v203
	v_exp_f32_e32 v206, v206
	v_exp_f32_e32 v205, v205
	v_exp_f32_e32 v207, v207
	v_exp_f32_e32 v192, v192
	v_exp_f32_e32 v194, v194
	v_exp_f32_e32 v193, v193
	v_exp_f32_e32 v196, v196
	v_exp_f32_e32 v195, v195
	v_exp_f32_e32 v198, v198
	v_exp_f32_e32 v197, v197
	v_exp_f32_e32 v199, v199
	v_exp_f32_e32 v166, v166
	s_waitcnt lgkmcnt(3)
	v_mfma_f32_32x32x16_bf16 v[80:95], v[64:67], v[134:137], 0
	v_exp_f32_e32 v167, v167
	v_exp_f32_e32 v163, v163
	v_exp_f32_e32 v168, v168
	v_mfma_f32_32x32x16_bf16 v[64:79], v[68:71], v[134:137], 0
	ds_read_b128 v[212:215], v221 offset:16384
	ds_read_b128 v[216:219], v221 offset:24576
	v_exp_f32_e32 v169, v169
	v_exp_f32_e32 v235, v162
	v_exp_f32_e32 v237, v164
	s_waitcnt lgkmcnt(2)
	v_mfma_f32_32x32x16_bf16 v[64:79], v[208:211], v[130:133], v[64:79]
	s_add_i32 s2, s42, 0xa000
	s_cmp_lg_u32 s61, 2
	s_cselect_b32 s2, s2, 0
	v_add_u32_e32 v240, s2, v178
	s_add_u32 s0, s82, 0x1bbc0100
	s_addc_u32 s1, s83, 0
	v_lshl_add_u64 v[238:239], v[150:151], 0, s[0:1]
	v_readfirstlane_b32 s2, v240
	s_mov_b32 m0, s2
	v_exp_f32_e32 v241, v165
	global_load_lds_dwordx4 v[238:239], off
	v_mfma_f32_32x32x16_bf16 v[80:95], v[188:191], v[130:133], v[80:95]
	ds_read_b128 v[188:191], v222 offset:16384
	ds_read_b128 v[208:211], v222 offset:24576
	v_exp_f32_e32 v243, v158
	v_exp_f32_e32 v244, v159
	v_exp_f32_e32 v245, v154
	s_waitcnt lgkmcnt(2)
	v_mfma_f32_32x32x16_bf16 v[64:79], v[216:219], v[126:129], v[64:79]
	v_add_f32_e32 v154, 0, v200
	v_add_f32_e32 v154, v202, v154
	v_add_f32_e32 v154, v201, v154
	v_add_f32_e32 v154, v204, v154
	v_add_f32_e32 v154, v203, v154
	v_add_f32_e32 v154, v206, v154
	v_mfma_f32_32x32x16_bf16 v[80:95], v[212:215], v[126:129], v[80:95]
	ds_read_b128 v[212:215], v177 offset:16512
	ds_read_b128 v[216:219], v177 offset:24704
	v_add_u32_e32 v177, s45, v182
	v_add_f32_e32 v154, v205, v154
	v_add_f32_e32 v154, v207, v154
	v_add_f32_e32 v154, v192, v154
	v_add_f32_e32 v154, v194, v154
	v_add_f32_e32 v154, v193, v154
	s_waitcnt lgkmcnt(2)
	v_mfma_f32_32x32x16_bf16 v[64:79], v[208:211], v[114:117], v[64:79]
	v_add_u32_e32 v242, 0x2000, v240
	s_add_u32 s0, s82, 0x1bbe0100
	s_addc_u32 s1, s83, 0
	v_lshl_add_u64 v[238:239], v[150:151], 0, s[0:1]
	v_readfirstlane_b32 s2, v242
	s_mov_b32 m0, s2
	v_add_f32_e32 v154, v196, v154
	global_load_lds_dwordx4 v[238:239], off
	v_add_f32_e32 v154, v195, v154
	v_add_f32_e32 v154, v198, v154
	v_mfma_f32_32x32x16_bf16 v[80:95], v[188:191], v[114:117], v[80:95]
	ds_read_b128 v[188:191], v220 offset:16512
	ds_read_b128 v[208:211], v220 offset:24704
	v_add_f32_e32 v154, v197, v154
	v_add_f32_e32 v154, v199, v154
	v_exp_f32_e32 v246, v160
	v_add_f32_e32 v154, v166, v154
	s_waitcnt lgkmcnt(2)
	v_mfma_f32_32x32x16_bf16 v[64:79], v[216:219], v[110:113], v[64:79]
	v_exp_f32_e32 v248, v161
	v_add_f32_e32 v154, v167, v154
	v_exp_f32_e32 v249, v156
	v_add_f32_e32 v154, v235, v154
	v_mfma_f32_32x32x16_bf16 v[80:95], v[212:215], v[110:113], v[80:95]
	ds_read_b128 v[212:215], v221 offset:16512
	ds_read_b128 v[216:219], v221 offset:24704
	v_exp_f32_e32 v250, v157
	v_add_f32_e32 v154, v163, v154
	v_add_f32_e32 v154, v246, v154
	v_exp_f32_e32 v251, v155
	s_waitcnt lgkmcnt(2)
	v_mfma_f32_32x32x16_bf16 v[64:79], v[208:211], v[106:109], v[64:79]
	v_add_u32_e32 v242, 0x4000, v240
	s_add_u32 s0, s82, 0x1bbc0000
	s_addc_u32 s1, s83, 0
	v_lshl_add_u64 v[238:239], v[152:153], 0, s[0:1]
	v_readfirstlane_b32 s2, v242
	s_mov_b32 m0, s2
	v_add_f32_e32 v154, v248, v154
	global_load_lds_dwordx4 v[238:239], off
	v_add_f32_e32 v154, v249, v154
	v_add_f32_e32 v154, v250, v154
	v_mfma_f32_32x32x16_bf16 v[80:95], v[188:191], v[106:109], v[80:95]
	ds_read_b128 v[188:191], v222 offset:16512
	ds_read_b128 v[208:211], v222 offset:24704
	v_add_f32_e32 v154, v245, v154
	v_add_f32_e32 v154, v251, v154
	v_add_f32_e32 v154, v168, v154
	v_add_f32_e32 v154, v169, v154
	v_add_f32_e32 v154, v237, v154
	v_add_f32_e32 v154, v241, v154
	s_waitcnt lgkmcnt(2)
	v_mfma_f32_32x32x16_bf16 v[64:79], v[216:219], v[102:105], v[64:79]
	v_add_f32_e32 v154, v243, v154
	v_cvt_pk_bf16_f32 v155, v201, v204
	v_cvt_pk_bf16_f32 v156, v203, v206
	v_cvt_pk_bf16_f32 v157, v205, v207
	v_cvt_pk_bf16_f32 v158, v192, v194
	v_cvt_pk_bf16_f32 v159, v193, v196
	v_mfma_f32_32x32x16_bf16 v[80:95], v[212:215], v[102:105], v[80:95]
	ds_read_b128 v[212:215], v177 offset:32768
	ds_read_b128 v[216:219], v177 offset:36864
	v_add_u32_e32 v177, s45, v183
	v_cvt_pk_bf16_f32 v160, v195, v198
	v_cvt_pk_bf16_f32 v161, v197, v199
	v_permlane32_swap_b32_e32 v155, v157
	v_permlane32_swap_b32_e32 v158, v160
	v_permlane32_swap_b32_e32 v159, v161
	s_waitcnt lgkmcnt(2)
	v_mfma_f32_32x32x16_bf16 v[64:79], v[208:211], v[98:101], v[64:79]
	v_add_u32_e32 v242, 0x6000, v240
	s_add_u32 s0, s82, 0x1bbe0000
	s_addc_u32 s1, s83, 0
	v_lshl_add_u64 v[238:239], v[152:153], 0, s[0:1]
	v_readfirstlane_b32 s2, v242
	s_mov_b32 m0, s2
	v_cvt_pk_bf16_f32 v162, v166, v167
	global_load_lds_dwordx4 v[238:239], off
	v_cvt_pk_bf16_f32 v163, v235, v163
	v_cvt_pk_bf16_f32 v164, v246, v248
	v_mfma_f32_32x32x16_bf16 v[80:95], v[188:191], v[98:101], v[80:95]
	ds_read_b128 v[188:191], v177 offset:32768
	ds_read_b128 v[208:211], v177 offset:36864
	v_add_u32_e32 v177, s45, v184
	v_cvt_pk_bf16_f32 v165, v249, v250
	v_cvt_pk_bf16_f32 v166, v245, v251
	v_cvt_pk_bf16_f32 v167, v168, v169
	v_cvt_pk_bf16_f32 v168, v237, v241
	v_cvt_pk_bf16_f32 v169, v243, v244
	s_waitcnt lgkmcnt(2)
; #define SBAR() __builtin_amdgcn_sched_barrier(0)
; template <int OFF> DI s16x4 tr_read(int vb) { s16x4 r; asm volatile("ds_read_b64_tr_b16 %0, %1 offset:%2" : "=&v"(r) : "v"(vb), "i"(OFF) : "memory"); return r; }
; DI void partialSM(f32x16& p0, f32x16& p1, float& m_reg, float& mn, float& alpha) {
;   constexpr float C = ATT_SCALE * 1.4426950408889634f;
;   float pmax = p0[0];
; #pragma unroll
;   for (int r = 1; r < 16; ++r) pmax = fmaxf(pmax, p0[r]);
; #pragma unroll
;   for (int r = 0; r < 16; ++r) pmax = fmaxf(pmax, p1[r]);
;   { auto rr = __builtin_amdgcn_permlane32_swap(__float_as_uint(pmax), __float_as_uint(pmax), false, false);
;     pmax = fmaxf(__uint_as_float(rr[0]), __uint_as_float(rr[1])); }
;   if (__builtin_expect(__all(pmax - m_reg <= ATT_THR / ATT_SCALE), 1)) { mn = m_reg; alpha = 1.f; }
; template <int D0> DI void pv_one(f32x16& od, int vb, bf16x8 pa0, bf16x8 pa1, bf16x8 pa2, bf16x8 pa3) {
;   const s16x4 l0 = tr_read<v_rd_off(D0, 0, 0)>(vb), h0 = tr_read<v_rd_off(D0, 0, 1)>(vb), l1 = tr_read<v_rd_off(D0, 1, 0)>(vb), h1 = tr_read<v_rd_off(D0, 1, 1)>(vb);
;   const s16x4 l2 = tr_read<v_rd_off(D0, 2, 0)>(vb), h2 = tr_read<v_rd_off(D0, 2, 1)>(vb), l3 = tr_read<v_rd_off(D0, 3, 0)>(vb), h3 = tr_read<v_rd_off(D0, 3, 1)>(vb);
;   asm volatile("s_waitcnt lgkmcnt(0)" ::: "memory"); SBAR();
;     ...
;   od = __builtin_amdgcn_mfma_f32_32x32x16_bf16(pa0, PK(l0, h0), od, 0, 0, 0);
;   od = __builtin_amdgcn_mfma_f32_32x32x16_bf16(pa1, PK(l1, h1), od, 0, 0, 0);
;   od = __builtin_amdgcn_mfma_f32_32x32x16_bf16(pa2, PK(l2, h2), od, 0, 0, 0);
;   od = __builtin_amdgcn_mfma_f32_32x32x16_bf16(pa3, PK(l3, h3), od, 0, 0, 0);
;     ...
; }
; DI void pv_d0(f32x16* o, int vb, bf16x8 pa0, bf16x8 pa1, bf16x8 pa2, bf16x8 pa3) {
;   pv_one<0>(o[0], vb, pa0, pa1, pa2, pa3); pv_one<1>(o[1], vb, pa0, pa1, pa2, pa3); pv_one<2>(o[2], vb, pa0, pa1, pa2, pa3); pv_one<3>(o[3], vb, pa0, pa1, pa2, pa3);
	v_mfma_f32_32x32x16_bf16 v[64:79], v[216:219], v[122:125], v[64:79]
	v_permlane32_swap_b32_e32 v162, v164
	v_permlane32_swap_b32_e32 v163, v165
	v_permlane32_swap_b32_e32 v166, v168
	v_permlane32_swap_b32_e32 v167, v169
	v_mfma_f32_32x32x16_bf16 v[80:95], v[212:215], v[122:125], v[80:95]
	ds_read_b128 v[212:215], v177 offset:32768
	ds_read_b128 v[216:219], v177 offset:36864
	v_add_u32_e32 v177, s45, v185
	s_waitcnt lgkmcnt(2)
	v_mfma_f32_32x32x16_bf16 v[64:79], v[208:211], v[142:145], v[64:79]
	v_add_u32_e32 v242, 0x8000, v240
	s_add_u32 s0, s82, 0x1fb44000
	s_addc_u32 s1, s83, 0
	v_lshl_add_u64 v[238:239], v[148:149], 0, s[0:1]
	v_readfirstlane_b32 s2, v242
	s_mov_b32 m0, s2
	s_nop 0
	global_load_lds_dwordx4 v[238:239], off
	s_movk_i32 s0, 0x410
	s_movk_i32 s1, 0x1800
	v_mfma_f32_32x32x16_bf16 v[80:95], v[188:191], v[142:145], v[80:95]
	ds_read_b128 v[188:191], v177 offset:32768
	ds_read_b128 v[208:211], v177 offset:36864
	s_waitcnt lgkmcnt(2)
	v_mfma_f32_32x32x16_bf16 v[64:79], v[216:219], v[118:121], v[64:79]
	v_mfma_f32_32x32x16_bf16 v[80:95], v[212:215], v[118:121], v[80:95]
	s_waitcnt lgkmcnt(0)
	v_mfma_f32_32x32x16_bf16 v[64:79], v[208:211], v[138:141], v[64:79]
	v_mfma_f32_32x32x16_bf16 v[80:95], v[188:191], v[138:141], v[80:95]
	s_mul_i32 s44, s13, 0xa000
	v_add_u32_e32 v177, s44, v174
	ds_read_b64_tr_b16 v[190:191], v177 offset:0
	ds_read_b64_tr_b16 v[192:193], v177 offset:0x800
	ds_read_b64_tr_b16 v[194:195], v177 offset:0x1000
	ds_read_b64_tr_b16 v[196:197], v177 offset:0x1800
	ds_read_b64_tr_b16 v[198:199], v177 offset:0x2000
	v_add_f32_e32 v188, v244, v154
	v_mov_b32_e32 v189, v188
	v_cvt_pk_bf16_f32 v154, v200, v202
	ds_read_b64_tr_b16 v[200:201], v177 offset:0x2800
	ds_read_b64_tr_b16 v[202:203], v177 offset:0x3000
	ds_read_b64_tr_b16 v[204:205], v177 offset:0x3800
	v_permlane32_swap_b32_e32 v188, v189
	v_permlane32_swap_b32_e32 v154, v156
	s_waitcnt lgkmcnt(6)
	v_max_f32_e32 v235, v81, v81
	v_mfma_f32_32x32x16_bf16 v[0:15], v[154:157], v[190:193], v[0:15]
	ds_read_b64_tr_b16 v[190:191], v177 offset:0x200
	ds_read_b64_tr_b16 v[192:193], v177 offset:0xa00
	v_max_f32_e32 v237, v80, v80
	v_max_f32_e32 v235, v237, v235
	v_max3_f32 v235, v235, v82, v83
	v_max3_f32 v235, v235, v84, v85
	v_max3_f32 v235, v235, v86, v87
	v_max3_f32 v235, v235, v88, v89
	s_waitcnt lgkmcnt(6)
	v_mfma_f32_32x32x16_bf16 v[0:15], v[158:161], v[194:197], v[0:15]
	ds_read_b64_tr_b16 v[194:195], v177 offset:0x1200
	ds_read_b64_tr_b16 v[196:197], v177 offset:0x1a00
	v_max3_f32 v235, v235, v90, v91
	v_max3_f32 v235, v235, v92, v93
	v_max3_f32 v235, v235, v94, v95
	v_max3_f32 v235, v235, v64, v65
	v_max3_f32 v235, v235, v66, v67
	v_max3_f32 v235, v235, v68, v69
	s_waitcnt lgkmcnt(6)
	v_mfma_f32_32x32x16_bf16 v[0:15], v[162:165], v[198:201], v[0:15]
	ds_read_b64_tr_b16 v[198:199], v177 offset:0x2200
	ds_read_b64_tr_b16 v[200:201], v177 offset:0x2a00
	v_max3_f32 v235, v235, v70, v71
	v_max3_f32 v235, v235, v72, v73
	v_max3_f32 v235, v235, v74, v75
	v_max3_f32 v235, v235, v76, v77
	v_max3_f32 v235, v235, v78, v79
	v_mov_b32_e32 v237, v235
	s_waitcnt lgkmcnt(6)
	v_mfma_f32_32x32x16_bf16 v[0:15], v[166:169], v[202:205], v[0:15]
	ds_read_b64_tr_b16 v[202:203], v177 offset:0x3200
	ds_read_b64_tr_b16 v[204:205], v177 offset:0x3a00
	v_permlane32_swap_b32_e32 v235, v237
	v_max_f32_e32 v237, v237, v237
	v_max_f32_e32 v235, v235, v235
	s_waitcnt lgkmcnt(6)
	v_mfma_f32_32x32x16_bf16 v[48:63], v[154:157], v[190:193], v[48:63]
	ds_read_b64_tr_b16 v[190:191], v177 offset:0x400
	ds_read_b64_tr_b16 v[192:193], v177 offset:0xc00
	s_waitcnt lgkmcnt(6)
	v_mfma_f32_32x32x16_bf16 v[48:63], v[158:161], v[194:197], v[48:63]
	ds_read_b64_tr_b16 v[194:195], v177 offset:0x1400
	ds_read_b64_tr_b16 v[196:197], v177 offset:0x1c00
	s_waitcnt lgkmcnt(6)
	v_mfma_f32_32x32x16_bf16 v[48:63], v[162:165], v[198:201], v[48:63]
	ds_read_b64_tr_b16 v[198:199], v177 offset:0x2400
	ds_read_b64_tr_b16 v[200:201], v177 offset:0x2c00
	s_waitcnt lgkmcnt(6)
	v_mfma_f32_32x32x16_bf16 v[48:63], v[166:169], v[202:205], v[48:63]
	ds_read_b64_tr_b16 v[202:203], v177 offset:0x3400
	ds_read_b64_tr_b16 v[204:205], v177 offset:0x3c00
	s_waitcnt lgkmcnt(6)
	v_mfma_f32_32x32x16_bf16 v[32:47], v[154:157], v[190:193], v[32:47]
	ds_read_b64_tr_b16 v[190:191], v177 offset:0x600
	ds_read_b64_tr_b16 v[192:193], v177 offset:0xe00
	s_waitcnt lgkmcnt(6)
	v_mfma_f32_32x32x16_bf16 v[32:47], v[158:161], v[194:197], v[32:47]
	ds_read_b64_tr_b16 v[194:195], v177 offset:0x1600
	ds_read_b64_tr_b16 v[196:197], v177 offset:0x1e00
	s_waitcnt lgkmcnt(6)
	v_mfma_f32_32x32x16_bf16 v[32:47], v[162:165], v[198:201], v[32:47]
	ds_read_b64_tr_b16 v[198:199], v177 offset:0x2600
	ds_read_b64_tr_b16 v[200:201], v177 offset:0x2e00
	s_waitcnt lgkmcnt(6)
	v_mfma_f32_32x32x16_bf16 v[32:47], v[166:169], v[202:205], v[32:47]
	ds_read_b64_tr_b16 v[202:203], v177 offset:0x3600
	ds_read_b64_tr_b16 v[204:205], v177 offset:0x3e00
	s_waitcnt lgkmcnt(6)
	v_mfma_f32_32x32x16_bf16 v[16:31], v[154:157], v[190:193], v[16:31]
	s_waitcnt lgkmcnt(4)
	v_mfma_f32_32x32x16_bf16 v[16:31], v[158:161], v[194:197], v[16:31]
	v_max_f32_e32 v160, v235, v237
	v_sub_f32_e32 v235, v160, v187
	s_waitcnt lgkmcnt(2)
	v_mfma_f32_32x32x16_bf16 v[16:31], v[162:165], v[198:201], v[16:31]
	s_waitcnt lgkmcnt(0)
	v_mfma_f32_32x32x16_bf16 v[16:31], v[166:169], v[202:205], v[16:31]
	v_cmp_ge_f32_e32 vcc, s65, v235
	s_cmp_eq_u64 vcc, exec
	s_waitcnt vmcnt(0)
	s_cselect_b64 s[38:39], -1, 0
	s_add_i32 s2, s12, -1
	s_cmp_ge_u32 s2, s52
	v_lshl_add_u64 v[158:159], v[150:151], 0, s[82:83]
	v_lshl_add_u64 v[156:157], v[152:153], 0, s[82:83]
	v_lshl_add_u64 v[154:155], v[148:149], 0, s[82:83]
	s_waitcnt vmcnt(0)
	s_barrier

; #define QK_FENCE() __builtin_amdgcn_sched_barrier(0x406)
; DI void partialSM(f32x16& p0, f32x16& p1, float& m_reg, float& mn, float& alpha) {
;     ...
;   else { mn = fmaxf(m_reg, pmax); alpha = __builtin_amdgcn_exp2f((m_reg - mn) * C); m_reg = mn; }
;   const float mnC = -mn * C;
; #pragma unroll
;   for (int r = 0; r < 16; ++r) p0[r] = fmaf(p0[r], C, mnC);
; #pragma unroll
;   for (int r = 0; r < 16; ++r) p1[r] = fmaf(p1[r], C, mnC);
; #pragma unroll
;   for (int r = 0; r < 16; ++r) p0[r] = __builtin_amdgcn_exp2f(p0[r]);
; }
; DI void finishSM(f32x16& p0, f32x16& p1, float alpha, float& l_reg, bf16x8& pa0, bf16x8& pa1, bf16x8& pa2, bf16x8& pa3) {
; #pragma unroll
;   for (int r = 0; r < 16; ++r) p1[r] = __builtin_amdgcn_exp2f(p1[r]);
;   float ps = 0;
; #pragma unroll
;   for (int r = 0; r < 16; ++r) ps += p0[r];
; #pragma unroll
;   for (int r = 0; r < 16; ++r) ps += p1[r];
;   { auto rr = __builtin_amdgcn_permlane32_swap(__float_as_uint(ps), __float_as_uint(ps), false, false);
;     ps = __uint_as_float(rr[0]) + __uint_as_float(rr[1]); }
;   l_reg = l_reg * alpha + ps;
; DI void qkt12(f32x16& p0, f32x16& p1, const char* Kt, const char* Rt, const int* ko, const int* ro, const bf16x8* qr) {
;   { const f32x16 z = {0.f, 0.f, 0.f, 0.f, 0.f, 0.f, 0.f, 0.f, 0.f, 0.f, 0.f, 0.f, 0.f, 0.f, 0.f, 0.f}; p0 = z; p1 = z; }
;   const char* kp[4] = {Kt + ko[0], Kt + ko[1], Kt + ko[2], Kt + ko[3]};
;   const char* rp[4] = {Rt + ro[0], Rt + ro[1], Rt + ro[2], Rt + ro[3]};
;   bf16x8 ka[2], kb[2];
;   ka[0] = *reinterpret_cast<const bf16x8*>(kp[0]); kb[0] = *reinterpret_cast<const bf16x8*>(kp[0] + 8192);
; #pragma unroll
;   for (int d0 = 0; d0 < 12; ++d0) {
;     if (d0 + 1 < 12) { const int d1 = d0 + 1;
;       if (d1 < 8) { ka[d1 & 1] = *reinterpret_cast<const bf16x8*>(kp[d1 & 3] + (d1 >> 2) * 128); kb[d1 & 1] = *reinterpret_cast<const bf16x8*>(kp[d1 & 3] + (d1 >> 2) * 128 + 8192); }
;       else { ka[d1 & 1] = *reinterpret_cast<const bf16x8*>(rp[d1 - 8]); kb[d1 & 1] = *reinterpret_cast<const bf16x8*>(rp[d1 - 8] + 4096); } }
;     QK_FENCE();
;     p0 = __builtin_amdgcn_mfma_f32_32x32x16_bf16(ka[d0 & 1], qr[d0], p0, 0, 0, 0);
;     p1 = __builtin_amdgcn_mfma_f32_32x32x16_bf16(kb[d0 & 1], qr[d0], p1, 0, 0, 0);
;     QK_FENCE();
;   }
.LBB0_128:
	s_add_i32 s2, s12, -1
	s_cmp_ge_u32 s2, s52
	s_cbranch_scc1 .Lattn_bb2_nodma
	v_cndmask_b32_e64 v160, v160, v187, s[38:39]
	s_add_i32 s2, s42, 0xa000
	s_cmp_lg_u32 s61, 2
	s_cselect_b32 s2, s2, 0
	s_add_i32 s6, s2, 16
	v_add_u32_e32 v213, s6, v176
	ds_read_b128 v[222:225], v213 offset:16384
	v_add_u32_e32 v230, s6, v179
	ds_read_b128 v[226:229], v213 offset:24576
	ds_read_b128 v[214:217], v230 offset:16384
	ds_read_b128 v[218:221], v230 offset:24576
	v_add_u32_e32 v231, s6, v180
	v_add_u32_e32 v234, s6, v181
	v_mul_f32_e32 v197, 0xbdd53b94, v160
	v_fmamk_f32 v161, v94, 0x3dd53b94, v197
	v_fmamk_f32 v194, v80, 0x3dd53b94, v197
	v_fmamk_f32 v196, v81, 0x3dd53b94, v197
	v_fmamk_f32 v192, v82, 0x3dd53b94, v197
	v_fmamk_f32 v195, v83, 0x3dd53b94, v197
	v_fmamk_f32 v187, v84, 0x3dd53b94, v197
	v_fmamk_f32 v193, v85, 0x3dd53b94, v197
	v_fmamk_f32 v169, v86, 0x3dd53b94, v197
	v_fmamk_f32 v190, v87, 0x3dd53b94, v197
	v_fmamk_f32 v166, v88, 0x3dd53b94, v197
	v_fmamk_f32 v168, v89, 0x3dd53b94, v197
	v_fmamk_f32 v164, v90, 0x3dd53b94, v197
	v_fmamk_f32 v167, v91, 0x3dd53b94, v197
	v_fmamk_f32 v162, v92, 0x3dd53b94, v197
	v_fmamk_f32 v165, v93, 0x3dd53b94, v197
	v_fmamk_f32 v163, v95, 0x3dd53b94, v197
	v_fmamk_f32 v208, v74, 0x3dd53b94, v197
	v_fmamk_f32 v209, v75, 0x3dd53b94, v197
	v_fmamk_f32 v198, v64, 0x3dd53b94, v197
	v_fmamk_f32 v199, v65, 0x3dd53b94, v197
	v_fmamk_f32 v200, v66, 0x3dd53b94, v197
	v_fmamk_f32 v201, v67, 0x3dd53b94, v197
	v_fmamk_f32 v202, v68, 0x3dd53b94, v197
	v_fmamk_f32 v203, v69, 0x3dd53b94, v197
	v_fmamk_f32 v204, v70, 0x3dd53b94, v197
	v_fmamk_f32 v205, v71, 0x3dd53b94, v197
	v_fmamk_f32 v206, v72, 0x3dd53b94, v197
	v_fmamk_f32 v207, v73, 0x3dd53b94, v197
	v_fmamk_f32 v210, v76, 0x3dd53b94, v197
	v_fmamk_f32 v211, v77, 0x3dd53b94, v197
	v_fmamk_f32 v212, v78, 0x3dd53b94, v197
	v_fmac_f32_e32 v197, 0x3dd53b94, v79
	v_exp_f32_e32 v161, v161
	s_waitcnt lgkmcnt(3)
	v_mfma_f32_32x32x16_bf16 v[80:95], v[222:225], v[134:137], 0
	v_exp_f32_e32 v194, v194
	v_exp_f32_e32 v196, v196
	v_exp_f32_e32 v192, v192
	s_waitcnt lgkmcnt(2)
	v_mfma_f32_32x32x16_bf16 v[64:79], v[226:229], v[134:137], 0
	ds_read_b128 v[222:225], v231 offset:16384
	ds_read_b128 v[226:229], v231 offset:24576
	v_exp_f32_e32 v195, v195
	v_exp_f32_e32 v187, v187
	v_exp_f32_e32 v193, v193
	s_waitcnt lgkmcnt(3)
	v_mfma_f32_32x32x16_bf16 v[80:95], v[214:217], v[130:133], v[80:95]
	v_add_u32_e32 v240, s44, v178
	v_exp_f32_e32 v169, v169
	v_readfirstlane_b32 s2, v240
	s_mov_b64 s[0:1], 0x1bc00100
	v_lshl_add_u64 v[238:239], v[158:159], 0, s[0:1]
	s_mov_b32 m0, s2
	v_exp_f32_e32 v190, v190
	global_load_lds_dwordx4 v[238:239], off
	s_waitcnt lgkmcnt(2)
	v_mfma_f32_32x32x16_bf16 v[64:79], v[218:221], v[130:133], v[64:79]
	ds_read_b128 v[214:217], v234 offset:16384
	ds_read_b128 v[218:221], v234 offset:24576
	v_exp_f32_e32 v166, v166
	v_exp_f32_e32 v168, v168
	v_exp_f32_e32 v164, v164
	s_waitcnt lgkmcnt(3)
	v_mfma_f32_32x32x16_bf16 v[80:95], v[222:225], v[126:129], v[80:95]
	v_exp_f32_e32 v167, v167
	v_exp_f32_e32 v162, v162
	v_exp_f32_e32 v165, v165
	s_waitcnt lgkmcnt(2)
	v_mfma_f32_32x32x16_bf16 v[64:79], v[226:229], v[126:129], v[64:79]
	ds_read_b128 v[222:225], v213 offset:16512
	ds_read_b128 v[226:229], v213 offset:24704
	v_add_u32_e32 v213, s6, v182
	v_exp_f32_e32 v163, v163
	v_exp_f32_e32 v198, v198
	s_waitcnt lgkmcnt(3)
	v_mfma_f32_32x32x16_bf16 v[80:95], v[214:217], v[114:117], v[80:95]
	v_add_u32_e32 v242, 0x2000, v240
	s_mov_b64 s[0:1], 0x1bc20100
	v_lshl_add_u64 v[238:239], v[158:159], 0, s[0:1]
	v_readfirstlane_b32 s2, v242
	s_mov_b32 m0, s2
	v_exp_f32_e32 v199, v199
	global_load_lds_dwordx4 v[238:239], off
	s_waitcnt lgkmcnt(2)
	v_mfma_f32_32x32x16_bf16 v[64:79], v[218:221], v[114:117], v[64:79]
	ds_read_b128 v[214:217], v230 offset:16512
	ds_read_b128 v[218:221], v230 offset:24704
	v_exp_f32_e32 v200, v200
	v_exp_f32_e32 v201, v201
	v_exp_f32_e32 v202, v202
	s_waitcnt lgkmcnt(3)
	v_mfma_f32_32x32x16_bf16 v[80:95], v[222:225], v[110:113], v[80:95]
	v_exp_f32_e32 v203, v203
	v_exp_f32_e32 v204, v204
	v_exp_f32_e32 v205, v205
	s_waitcnt lgkmcnt(2)
	v_mfma_f32_32x32x16_bf16 v[64:79], v[226:229], v[110:113], v[64:79]
	ds_read_b128 v[222:225], v231 offset:16512
	ds_read_b128 v[226:229], v231 offset:24704
	v_exp_f32_e32 v206, v206
	v_exp_f32_e32 v207, v207
	v_exp_f32_e32 v210, v210
	s_waitcnt lgkmcnt(3)
	v_mfma_f32_32x32x16_bf16 v[80:95], v[214:217], v[106:109], v[80:95]
	v_add_u32_e32 v242, 0x4000, v240
	s_mov_b64 s[0:1], 0x1bc00000
	v_lshl_add_u64 v[238:239], v[156:157], 0, s[0:1]
	v_readfirstlane_b32 s2, v242
	s_mov_b32 m0, s2
	v_exp_f32_e32 v211, v211
	global_load_lds_dwordx4 v[238:239], off
	s_waitcnt lgkmcnt(2)
	v_mfma_f32_32x32x16_bf16 v[64:79], v[218:221], v[106:109], v[64:79]
	ds_read_b128 v[214:217], v234 offset:16512
	ds_read_b128 v[218:221], v234 offset:24704
	v_exp_f32_e32 v212, v212
	v_exp_f32_e32 v235, v208
	v_exp_f32_e32 v237, v197
	s_waitcnt lgkmcnt(3)
	v_mfma_f32_32x32x16_bf16 v[80:95], v[222:225], v[102:105], v[80:95]
	v_add_f32_e32 v197, 0, v194
	v_add_f32_e32 v197, v196, v197
	v_add_f32_e32 v197, v192, v197
	v_add_f32_e32 v197, v195, v197
	v_add_f32_e32 v197, v187, v197
	v_add_f32_e32 v197, v193, v197
	s_waitcnt lgkmcnt(2)
	v_mfma_f32_32x32x16_bf16 v[64:79], v[226:229], v[102:105], v[64:79]
	ds_read_b128 v[222:225], v213 offset:32768
	ds_read_b128 v[226:229], v213 offset:36864
	v_add_u32_e32 v213, s6, v183
	v_add_f32_e32 v197, v169, v197
	v_add_f32_e32 v197, v190, v197
	v_add_f32_e32 v197, v166, v197
	v_add_f32_e32 v197, v168, v197
	v_add_f32_e32 v197, v164, v197
	s_waitcnt lgkmcnt(3)
; #define SBAR() __builtin_amdgcn_sched_barrier(0)
; template <int OFF> DI s16x4 tr_read(int vb) { s16x4 r; asm volatile("ds_read_b64_tr_b16 %0, %1 offset:%2" : "=&v"(r) : "v"(vb), "i"(OFF) : "memory"); return r; }
; DI void finishSM(f32x16& p0, f32x16& p1, float alpha, float& l_reg, bf16x8& pa0, bf16x8& pa1, bf16x8& pa2, bf16x8& pa3) {
; #pragma unroll
;   for (int r = 0; r < 16; ++r) p1[r] = __builtin_amdgcn_exp2f(p1[r]);
;   float ps = 0;
; #pragma unroll
;   for (int r = 0; r < 16; ++r) ps += p0[r];
; #pragma unroll
;   for (int r = 0; r < 16; ++r) ps += p1[r];
;   { auto rr = __builtin_amdgcn_permlane32_swap(__float_as_uint(ps), __float_as_uint(ps), false, false);
;     ps = __uint_as_float(rr[0]) + __uint_as_float(rr[1]); }
;   l_reg = l_reg * alpha + ps;
;     ...
;   PK4(p0, 0, pa0); PK4(p0, 8, pa1); PK4(p1, 0, pa2); PK4(p1, 8, pa3);
; template <int D0> DI void pv_one(f32x16& od, int vb, bf16x8 pa0, bf16x8 pa1, bf16x8 pa2, bf16x8 pa3) {
;   const s16x4 l0 = tr_read<v_rd_off(D0, 0, 0)>(vb), h0 = tr_read<v_rd_off(D0, 0, 1)>(vb), l1 = tr_read<v_rd_off(D0, 1, 0)>(vb), h1 = tr_read<v_rd_off(D0, 1, 1)>(vb);
;   const s16x4 l2 = tr_read<v_rd_off(D0, 2, 0)>(vb), h2 = tr_read<v_rd_off(D0, 2, 1)>(vb), l3 = tr_read<v_rd_off(D0, 3, 0)>(vb), h3 = tr_read<v_rd_off(D0, 3, 1)>(vb);
;   asm volatile("s_waitcnt lgkmcnt(0)" ::: "memory"); SBAR();
;     ...
;   od = __builtin_amdgcn_mfma_f32_32x32x16_bf16(pa0, PK(l0, h0), od, 0, 0, 0);
;   od = __builtin_amdgcn_mfma_f32_32x32x16_bf16(pa1, PK(l1, h1), od, 0, 0, 0);
;   od = __builtin_amdgcn_mfma_f32_32x32x16_bf16(pa2, PK(l2, h2), od, 0, 0, 0);
;   od = __builtin_amdgcn_mfma_f32_32x32x16_bf16(pa3, PK(l3, h3), od, 0, 0, 0);
	v_mfma_f32_32x32x16_bf16 v[80:95], v[214:217], v[98:101], v[80:95]
	v_add_u32_e32 v242, 0x6000, v240
	s_mov_b64 s[0:1], 0x1bc20000
	v_lshl_add_u64 v[238:239], v[156:157], 0, s[0:1]
	v_readfirstlane_b32 s2, v242
	s_mov_b32 m0, s2
	v_add_f32_e32 v197, v167, v197
	global_load_lds_dwordx4 v[238:239], off
	v_add_f32_e32 v197, v162, v197
	v_add_f32_e32 v197, v165, v197
	s_waitcnt lgkmcnt(2)
	v_mfma_f32_32x32x16_bf16 v[64:79], v[218:221], v[98:101], v[64:79]
	ds_read_b128 v[214:217], v213 offset:32768
	ds_read_b128 v[218:221], v213 offset:36864
	v_add_u32_e32 v213, s6, v184
	v_add_f32_e32 v197, v161, v197
	v_add_f32_e32 v197, v163, v197
	v_add_f32_e32 v197, v198, v197
	v_add_f32_e32 v197, v199, v197
	v_add_f32_e32 v197, v200, v197
	s_waitcnt lgkmcnt(3)
	v_mfma_f32_32x32x16_bf16 v[80:95], v[222:225], v[122:125], v[80:95]
	v_add_f32_e32 v197, v201, v197
	v_add_f32_e32 v197, v202, v197
	v_add_f32_e32 v197, v203, v197
	v_add_f32_e32 v197, v204, v197
	v_exp_f32_e32 v241, v209
	s_waitcnt lgkmcnt(2)
	v_mfma_f32_32x32x16_bf16 v[64:79], v[226:229], v[122:125], v[64:79]
	ds_read_b128 v[222:225], v213 offset:32768
	ds_read_b128 v[226:229], v213 offset:36864
	v_add_u32_e32 v213, s6, v185
	v_add_f32_e32 v197, v205, v197
	v_add_f32_e32 v197, v206, v197
	v_add_f32_e32 v197, v207, v197
	v_add_f32_e32 v197, v235, v197
	v_add_f32_e32 v197, v241, v197
	s_waitcnt lgkmcnt(3)
	v_mfma_f32_32x32x16_bf16 v[80:95], v[214:217], v[142:145], v[80:95]
	v_add_u32_e32 v242, 0x8000, v240
	s_mov_b64 s[0:1], 0x1fb46000
	v_lshl_add_u64 v[238:239], v[154:155], 0, s[0:1]
	v_readfirstlane_b32 s2, v242
	s_mov_b32 m0, s2
	v_add_f32_e32 v197, v210, v197
	global_load_lds_dwordx4 v[238:239], off
	s_movk_i32 s0, 0x410
	s_movk_i32 s1, 0x1800
	v_add_f32_e32 v197, v211, v197
	v_add_f32_e32 v197, v212, v197
	s_waitcnt lgkmcnt(2)
	v_mfma_f32_32x32x16_bf16 v[64:79], v[218:221], v[142:145], v[64:79]
	ds_read_b128 v[214:217], v213 offset:32768
	ds_read_b128 v[218:221], v213 offset:36864
	v_add_f32_e32 v208, v237, v197
	v_mov_b32_e32 v209, v208
	v_cvt_pk_bf16_f32 v194, v194, v196
	v_cvt_pk_bf16_f32 v195, v192, v195
	v_permlane32_swap_b32_e32 v208, v209
	v_cvt_pk_bf16_f32 v196, v187, v193
	s_waitcnt lgkmcnt(3)
	v_mfma_f32_32x32x16_bf16 v[80:95], v[222:225], v[118:121], v[80:95]
	v_cvt_pk_bf16_f32 v197, v169, v190
	v_cvt_pk_bf16_f32 v166, v166, v168
	v_cvt_pk_bf16_f32 v167, v164, v167
	v_cvt_pk_bf16_f32 v168, v162, v165
	v_cvt_pk_bf16_f32 v169, v161, v163
	v_cvt_pk_bf16_f32 v162, v198, v199
	s_waitcnt lgkmcnt(2)
	v_mfma_f32_32x32x16_bf16 v[64:79], v[226:229], v[118:121], v[64:79]
	v_cvt_pk_bf16_f32 v163, v200, v201
	v_cvt_pk_bf16_f32 v164, v202, v203
	v_cvt_pk_bf16_f32 v165, v204, v205
	v_cvt_pk_bf16_f32 v198, v206, v207
	v_cvt_pk_bf16_f32 v199, v235, v241
	v_cvt_pk_bf16_f32 v200, v210, v211
	s_waitcnt lgkmcnt(1)
	v_mfma_f32_32x32x16_bf16 v[80:95], v[214:217], v[138:141], v[80:95]
	v_cvt_pk_bf16_f32 v201, v212, v237
	v_permlane32_swap_b32_e32 v194, v196
	v_permlane32_swap_b32_e32 v195, v197
	v_permlane32_swap_b32_e32 v166, v168
	v_permlane32_swap_b32_e32 v167, v169
	v_permlane32_swap_b32_e32 v162, v164
	s_waitcnt lgkmcnt(0)
	v_mfma_f32_32x32x16_bf16 v[64:79], v[218:221], v[138:141], v[64:79]
	v_add_u32_e32 v161, s42, v174
	ds_read_b64_tr_b16 v[202:203], v161 offset:0
	ds_read_b64_tr_b16 v[204:205], v161 offset:0x800
	ds_read_b64_tr_b16 v[210:211], v161 offset:0x1000
	ds_read_b64_tr_b16 v[212:213], v161 offset:0x1800
	ds_read_b64_tr_b16 v[214:215], v161 offset:0x2000
	ds_read_b64_tr_b16 v[216:217], v161 offset:0x2800
	ds_read_b64_tr_b16 v[218:219], v161 offset:0x3000
	ds_read_b64_tr_b16 v[220:221], v161 offset:0x3800
	v_permlane32_swap_b32_e32 v163, v165
	v_permlane32_swap_b32_e32 v198, v200
	v_permlane32_swap_b32_e32 v199, v201
	v_max_f32_e32 v235, v81, v81
	v_max_f32_e32 v237, v80, v80
	s_waitcnt lgkmcnt(6)
; #define SBAR() __builtin_amdgcn_sched_barrier(0)
; template <int OFF> DI s16x4 tr_read(int vb) { s16x4 r; asm volatile("ds_read_b64_tr_b16 %0, %1 offset:%2" : "=&v"(r) : "v"(vb), "i"(OFF) : "memory"); return r; }
; DI void partialSM(f32x16& p0, f32x16& p1, float& m_reg, float& mn, float& alpha) {
;   constexpr float C = ATT_SCALE * 1.4426950408889634f;
;   float pmax = p0[0];
; #pragma unroll
;   for (int r = 1; r < 16; ++r) pmax = fmaxf(pmax, p0[r]);
; #pragma unroll
;   for (int r = 0; r < 16; ++r) pmax = fmaxf(pmax, p1[r]);
;   { auto rr = __builtin_amdgcn_permlane32_swap(__float_as_uint(pmax), __float_as_uint(pmax), false, false);
;     pmax = fmaxf(__uint_as_float(rr[0]), __uint_as_float(rr[1])); }
;   if (__builtin_expect(__all(pmax - m_reg <= ATT_THR / ATT_SCALE), 1)) { mn = m_reg; alpha = 1.f; }
; template <int D0> DI void pv_one(f32x16& od, int vb, bf16x8 pa0, bf16x8 pa1, bf16x8 pa2, bf16x8 pa3) {
;   const s16x4 l0 = tr_read<v_rd_off(D0, 0, 0)>(vb), h0 = tr_read<v_rd_off(D0, 0, 1)>(vb), l1 = tr_read<v_rd_off(D0, 1, 0)>(vb), h1 = tr_read<v_rd_off(D0, 1, 1)>(vb);
;   const s16x4 l2 = tr_read<v_rd_off(D0, 2, 0)>(vb), h2 = tr_read<v_rd_off(D0, 2, 1)>(vb), l3 = tr_read<v_rd_off(D0, 3, 0)>(vb), h3 = tr_read<v_rd_off(D0, 3, 1)>(vb);
;   asm volatile("s_waitcnt lgkmcnt(0)" ::: "memory"); SBAR();
;     ...
;   od = __builtin_amdgcn_mfma_f32_32x32x16_bf16(pa0, PK(l0, h0), od, 0, 0, 0);
;   od = __builtin_amdgcn_mfma_f32_32x32x16_bf16(pa1, PK(l1, h1), od, 0, 0, 0);
;   od = __builtin_amdgcn_mfma_f32_32x32x16_bf16(pa2, PK(l2, h2), od, 0, 0, 0);
;   od = __builtin_amdgcn_mfma_f32_32x32x16_bf16(pa3, PK(l3, h3), od, 0, 0, 0);
;     ...
; }
; DI void pv_d0(f32x16* o, int vb, bf16x8 pa0, bf16x8 pa1, bf16x8 pa2, bf16x8 pa3) {
;   pv_one<0>(o[0], vb, pa0, pa1, pa2, pa3); pv_one<1>(o[1], vb, pa0, pa1, pa2, pa3); pv_one<2>(o[2], vb, pa0, pa1, pa2, pa3); pv_one<3>(o[3], vb, pa0, pa1, pa2, pa3);
	v_mfma_f32_32x32x16_bf16 v[0:15], v[194:197], v[202:205], v[0:15]
	ds_read_b64_tr_b16 v[202:203], v161 offset:0x200
	ds_read_b64_tr_b16 v[204:205], v161 offset:0xa00
	v_max_f32_e32 v235, v237, v235
	v_max3_f32 v235, v235, v82, v83
	v_max3_f32 v235, v235, v84, v85
	v_max3_f32 v235, v235, v86, v87
	v_max3_f32 v235, v235, v88, v89
	v_max3_f32 v235, v235, v90, v91
	s_waitcnt lgkmcnt(6)
	v_mfma_f32_32x32x16_bf16 v[0:15], v[166:169], v[210:213], v[0:15]
	ds_read_b64_tr_b16 v[210:211], v161 offset:0x1200
	ds_read_b64_tr_b16 v[212:213], v161 offset:0x1a00
	v_max3_f32 v235, v235, v92, v93
	v_max3_f32 v235, v235, v94, v95
	v_max3_f32 v235, v235, v64, v65
	v_max3_f32 v235, v235, v66, v67
	v_max3_f32 v235, v235, v68, v69
	v_max3_f32 v235, v235, v70, v71
	s_waitcnt lgkmcnt(6)
	v_mfma_f32_32x32x16_bf16 v[0:15], v[162:165], v[214:217], v[0:15]
	ds_read_b64_tr_b16 v[214:215], v161 offset:0x2200
	ds_read_b64_tr_b16 v[216:217], v161 offset:0x2a00
	v_max3_f32 v235, v235, v72, v73
	v_max3_f32 v235, v235, v74, v75
	v_max3_f32 v235, v235, v76, v77
	v_max3_f32 v235, v235, v78, v79
	v_mov_b32_e32 v237, v235
	s_waitcnt lgkmcnt(6)
	v_mfma_f32_32x32x16_bf16 v[0:15], v[198:201], v[218:221], v[0:15]
	ds_read_b64_tr_b16 v[218:219], v161 offset:0x3200
	ds_read_b64_tr_b16 v[220:221], v161 offset:0x3a00
	v_permlane32_swap_b32_e32 v235, v237
	v_max_f32_e32 v237, v237, v237
	v_max_f32_e32 v235, v235, v235
	s_waitcnt lgkmcnt(6)
	v_mfma_f32_32x32x16_bf16 v[48:63], v[194:197], v[202:205], v[48:63]
	ds_read_b64_tr_b16 v[202:203], v161 offset:0x400
	ds_read_b64_tr_b16 v[204:205], v161 offset:0xc00
	s_waitcnt lgkmcnt(6)
	v_mfma_f32_32x32x16_bf16 v[48:63], v[166:169], v[210:213], v[48:63]
	ds_read_b64_tr_b16 v[210:211], v161 offset:0x1400
	ds_read_b64_tr_b16 v[212:213], v161 offset:0x1c00
	s_waitcnt lgkmcnt(6)
	v_mfma_f32_32x32x16_bf16 v[48:63], v[162:165], v[214:217], v[48:63]
	ds_read_b64_tr_b16 v[214:215], v161 offset:0x2400
	ds_read_b64_tr_b16 v[216:217], v161 offset:0x2c00
	s_waitcnt lgkmcnt(6)
	v_mfma_f32_32x32x16_bf16 v[48:63], v[198:201], v[218:221], v[48:63]
	ds_read_b64_tr_b16 v[218:219], v161 offset:0x3400
	ds_read_b64_tr_b16 v[220:221], v161 offset:0x3c00
	s_waitcnt lgkmcnt(6)
	v_mfma_f32_32x32x16_bf16 v[32:47], v[194:197], v[202:205], v[32:47]
	ds_read_b64_tr_b16 v[202:203], v161 offset:0x600
	ds_read_b64_tr_b16 v[204:205], v161 offset:0xe00
	s_waitcnt lgkmcnt(6)
	v_mfma_f32_32x32x16_bf16 v[32:47], v[166:169], v[210:213], v[32:47]
	ds_read_b64_tr_b16 v[210:211], v161 offset:0x1600
	ds_read_b64_tr_b16 v[212:213], v161 offset:0x1e00
	s_waitcnt lgkmcnt(6)
	v_mfma_f32_32x32x16_bf16 v[32:47], v[162:165], v[214:217], v[32:47]
	ds_read_b64_tr_b16 v[214:215], v161 offset:0x2600
	ds_read_b64_tr_b16 v[216:217], v161 offset:0x2e00
	s_waitcnt lgkmcnt(6)
	v_mfma_f32_32x32x16_bf16 v[32:47], v[198:201], v[218:221], v[32:47]
	ds_read_b64_tr_b16 v[218:219], v161 offset:0x3600
	ds_read_b64_tr_b16 v[220:221], v161 offset:0x3e00
	v_max_f32_e32 v161, v235, v237
	v_sub_f32_e32 v237, v235, v160
	s_waitcnt lgkmcnt(6)
	v_mfma_f32_32x32x16_bf16 v[16:31], v[194:197], v[202:205], v[16:31]
	s_waitcnt lgkmcnt(4)
	v_mfma_f32_32x32x16_bf16 v[16:31], v[166:169], v[210:213], v[16:31]
	s_waitcnt lgkmcnt(2)
	v_mfma_f32_32x32x16_bf16 v[16:31], v[162:165], v[214:217], v[16:31]
	s_waitcnt lgkmcnt(0)
	v_mfma_f32_32x32x16_bf16 v[16:31], v[198:201], v[218:221], v[16:31]
	v_cmp_ge_f32_e32 vcc, s65, v237
	s_cmp_eq_u64 vcc, exec
	s_cselect_b64 s[38:39], -1, 0
	s_cmp_ge_u32 s12, s52
	s_cselect_b64 s[42:43], -1, 0
	s_and_b64 vcc, exec, s[42:43]
	s_waitcnt vmcnt(0)
	s_waitcnt vmcnt(0)
	s_barrier
	s_branch .Lattn_bb2_join

; DI void partialSM(f32x16& p0, f32x16& p1, float& m_reg, float& mn, float& alpha) {
;     ...
;   if (__builtin_expect(__all(pmax - m_reg <= ATT_THR / ATT_SCALE), 1)) { mn = m_reg; alpha = 1.f; }
;   else { mn = fmaxf(m_reg, pmax); alpha = __builtin_amdgcn_exp2f((m_reg - mn) * C); m_reg = mn; }
.Lattn_bb2_join:
.LBB0_130:
	v_max_f32_e32 v154, v160, v160
	v_max_f32_e32 v154, v154, v161
	v_sub_f32_e32 v155, v160, v154
	v_mul_f32_e32 v155, 0x3dd53b94, v155
	v_exp_f32_e32 v155, v155
	s_nop 0
	v_cndmask_b32_e64 v190, v155, 1.0, s[38:39]
	v_cmp_gt_f32_e32 vcc, 1.0, v190
	s_cbranch_vccz .LBB0_134
	s_and_saveexec_b64 s[6:7], s[36:37]
	ds_write_b32 v172, v190 offset:128
	s_or_b64 exec, exec, s[6:7]
	s_waitcnt lgkmcnt(0)
	v_add_u32_e32 v155, v147, v96
	ds_read_b128 v[156:159], v155 offset:224
	ds_read_b128 v[162:165], v155 offset:192
	ds_read_b128 v[166:169], v155 offset:160
	ds_read_b128 v[192:195], v155 offset:128
	s_waitcnt lgkmcnt(0)
	v_pk_mul_f32 v[12:13], v[12:13], v[156:157]
	v_pk_mul_f32 v[8:9], v[8:9], v[162:163]
	v_pk_mul_f32 v[4:5], v[4:5], v[166:167]
	v_pk_mul_f32 v[14:15], v[14:15], v[158:159]
	v_pk_mul_f32 v[10:11], v[10:11], v[164:165]
	v_pk_mul_f32 v[6:7], v[6:7], v[168:169]
	v_pk_mul_f32 v[2:3], v[2:3], v[194:195]
	v_pk_mul_f32 v[0:1], v[0:1], v[192:193]
	v_pk_mul_f32 v[60:61], v[60:61], v[156:157]
	v_pk_mul_f32 v[56:57], v[56:57], v[162:163]
	v_pk_mul_f32 v[52:53], v[52:53], v[166:167]
	v_pk_mul_f32 v[62:63], v[62:63], v[158:159]
	v_pk_mul_f32 v[58:59], v[58:59], v[164:165]
	v_pk_mul_f32 v[54:55], v[54:55], v[168:169]
	v_pk_mul_f32 v[50:51], v[50:51], v[194:195]
	v_pk_mul_f32 v[48:49], v[48:49], v[192:193]
	v_pk_mul_f32 v[44:45], v[44:45], v[156:157]
	v_pk_mul_f32 v[40:41], v[40:41], v[162:163]
	v_pk_mul_f32 v[36:37], v[36:37], v[166:167]
	v_pk_mul_f32 v[46:47], v[46:47], v[158:159]
	v_pk_mul_f32 v[42:43], v[42:43], v[164:165]
	v_pk_mul_f32 v[38:39], v[38:39], v[168:169]
	v_pk_mul_f32 v[34:35], v[34:35], v[194:195]
	v_pk_mul_f32 v[32:33], v[32:33], v[192:193]
	v_pk_mul_f32 v[28:29], v[28:29], v[156:157]
	v_pk_mul_f32 v[24:25], v[24:25], v[162:163]
	v_pk_mul_f32 v[20:21], v[20:21], v[166:167]
	v_pk_mul_f32 v[30:31], v[30:31], v[158:159]
	v_pk_mul_f32 v[26:27], v[26:27], v[164:165]
	v_pk_mul_f32 v[22:23], v[22:23], v[168:169]
	v_pk_mul_f32 v[18:19], v[18:19], v[194:195]
	v_pk_mul_f32 v[16:17], v[16:17], v[192:193]
